# grid barriers after P1/P2/P3: XCC last arriver adds to per-XCC top-counter copies, all WGs poll own copy (two serial hops fewer)
# speedup vs baseline: 1.5169x; 1.0129x over previous
.LBB0_665:
	s_waitcnt vmcnt(0)
	s_waitcnt lgkmcnt(0)
	s_barrier
	s_mov_b64 s[0:1], exec
	v_readlane_b32 s2, v244, 4
	v_readlane_b32 s3, v244, 5
	s_and_b64 s[2:3], s[0:1], s[2:3]
	s_mov_b64 exec, s[2:3]
	s_cbranch_execz .LBB0_717
	v_readlane_b32 s4, v243, 10
	v_readlane_b32 s5, v243, 11
	v_readlane_b32 s2, v242, 40
	s_waitcnt vmcnt(0) expcnt(0) lgkmcnt(0)
	ds_read_b32 v4, v155 offset:16
	ds_read_b32 v2, v155 offset:20
	v_mov_b32_e32 v5, 1
	s_mul_i32 s2, s2, 3
	s_add_i32 s3, s2, 2
	s_add_i32 s2, s2, 1
	global_atomic_add v5, v155, v5, s[4:5] sc0
	s_add_u32 s6, s4, 0x2240
	s_addc_u32 s7, s5, 0
	s_mov_b32 s10, 0
	s_waitcnt lgkmcnt(0)
	v_mul_lo_u32 v6, v4, s3
	v_mul_lo_u32 v7, v2, s2
	s_waitcnt vmcnt(0)
	v_add_u32_e32 v5, 1, v5
	v_cmp_ne_u32_e32 vcc, v5, v6
	s_cbranch_vccnz .LFB_b1_poll
	s_mov_b64 s[12:13], exec
	s_mov_b64 exec, 0xffff
	v_mbcnt_lo_u32_b32 v8, -1, 0
	v_mov_b32_e32 v9, 1
	v_lshlrev_b32_e32 v8, 8, v8
	v_add_u32_e32 v8, 0x3640, v8
	global_atomic_add v8, v9, s[96:97]
	s_mov_b64 exec, s[12:13]
.LFB_b1_poll:
	global_load_dword v5, v155, s[6:7] sc1
	s_waitcnt vmcnt(0)
	v_cmp_ge_u32_e32 vcc, v5, v7
	s_cbranch_vccnz .LFB_b1_done
	s_sleep 1
	s_add_i32 s10, s10, 1
	s_cmp_lt_u32 s10, 0x40000
	s_cbranch_scc1 .LFB_b1_poll
.LFB_b1_done:
	buffer_inv sc1
	s_waitcnt vmcnt(0)

.LBB0_863:
	s_waitcnt vmcnt(0)
	s_waitcnt lgkmcnt(0)
	s_barrier
	s_mov_b64 s[0:1], exec
	v_readlane_b32 s2, v244, 4
	v_readlane_b32 s3, v244, 5
	s_and_b64 s[2:3], s[0:1], s[2:3]
	s_mov_b64 exec, s[2:3]
	s_cbranch_execz .LBB0_915
	v_readlane_b32 s4, v243, 10
	v_readlane_b32 s5, v243, 11
	v_readlane_b32 s2, v242, 40
	s_waitcnt vmcnt(0) expcnt(0) lgkmcnt(0)
	ds_read_b32 v4, v155 offset:16
	ds_read_b32 v2, v155 offset:20
	v_mov_b32_e32 v5, 1
	s_mul_i32 s2, s2, 3
	s_add_i32 s3, s2, 3
	s_add_i32 s2, s2, 2
	global_atomic_add v5, v155, v5, s[4:5] sc0
	s_add_u32 s6, s4, 0x2240
	s_addc_u32 s7, s5, 0
	s_mov_b32 s10, 0
	s_waitcnt lgkmcnt(0)
	v_mul_lo_u32 v6, v4, s3
	v_mul_lo_u32 v7, v2, s2
	s_waitcnt vmcnt(0)
	v_add_u32_e32 v5, 1, v5
	v_cmp_ne_u32_e32 vcc, v5, v6
	s_cbranch_vccnz .LFB_b2_poll
	buffer_wbl2 sc1
	s_waitcnt vmcnt(0)
	s_mov_b64 s[12:13], exec
	s_mov_b64 exec, 0xffff
	v_mbcnt_lo_u32_b32 v8, -1, 0
	v_mov_b32_e32 v9, 1
	v_lshlrev_b32_e32 v8, 8, v8
	v_add_u32_e32 v8, 0x3640, v8
	global_atomic_add v8, v9, s[96:97]
	s_mov_b64 exec, s[12:13]

.LBB0_961:
	s_waitcnt vmcnt(0)
	s_waitcnt lgkmcnt(0)
	s_barrier
	s_mov_b64 s[0:1], exec
	v_readlane_b32 s2, v244, 4
	v_readlane_b32 s3, v244, 5
	s_and_b64 s[2:3], s[0:1], s[2:3]
	s_mov_b64 exec, s[2:3]
	s_cbranch_execz .LBB0_430
	v_readlane_b32 s4, v243, 10
	v_readlane_b32 s5, v243, 11
	v_readlane_b32 s2, v242, 40
	s_waitcnt vmcnt(0) expcnt(0) lgkmcnt(0)
	ds_read_b32 v4, v155 offset:16
	ds_read_b32 v2, v155 offset:20
	v_mov_b32_e32 v5, 1
	s_mul_i32 s2, s2, 3
	s_add_i32 s3, s2, 4
	s_add_i32 s2, s2, 3
	global_atomic_add v5, v155, v5, s[4:5] sc0
	s_add_u32 s6, s4, 0x2240
	s_addc_u32 s7, s5, 0
	s_mov_b32 s10, 0
	s_waitcnt lgkmcnt(0)
	v_mul_lo_u32 v6, v4, s3
	v_mul_lo_u32 v7, v2, s2
	s_waitcnt vmcnt(0)
	v_add_u32_e32 v5, 1, v5
	v_cmp_ne_u32_e32 vcc, v5, v6
	s_cbranch_vccnz .LFB_b3_poll
	s_mov_b64 s[12:13], exec
	s_mov_b64 exec, 0xffff
	v_mbcnt_lo_u32_b32 v8, -1, 0
	v_mov_b32_e32 v9, 1
	v_lshlrev_b32_e32 v8, 8, v8
	v_add_u32_e32 v8, 0x3640, v8
	global_atomic_add v8, v9, s[96:97]
	s_mov_b64 exec, s[12:13]

.LFB_b3_done:
	buffer_inv sc1
	s_waitcnt vmcnt(0)
	s_branch .LBB0_430
